# scan: chunk-group ready flag read one chunk ahead (no exposed poll round trip at group boundaries)
# speedup vs baseline: 1.0148x; 1.0013x over previous
; __device__ __forceinline__ int ltid() { int t = threadIdx.x; asm volatile("" : "+v"(t)); return t; }
; __device__ __forceinline__ void scan_chunked(const Params& p, unsigned char* smem, int bh, f32x16 (&S)[4], const int c_begin, const int c_end) {
;   u16* DX = (u16*)(p.ws + OFF_DX); const u16* TA = (const u16*)(p.ws + OFF_EXTRA);
;   const int tid = ltid(), lane = tid & 63, wave = tid >> 6;
;   const int l31 = lane & 31, hf = lane >> 5;
;   u16* sk = (u16*)smem;
;   u16* sq = sk + 64 * 136;
;   u16* sT = sq + 64 * 136;
;   u16* sA = sT + 64 * 72;
;   float* sSC = (float*)(sA + 64 * 72);
;   u32x4 pk[4], pq[4], pT[2], pA[2]; uint2 pv[8]; float psc;
;     ...
;       u32x4 id1 = {0u, 0u, 0u, 0u}, id2 = {0u, 0u, 0u, 0u};
;       {
;         const int l15 = l31 & 15;
;         const int jsel = (((l15 >> 2) & 1) == hf) ? (4 * (l15 >> 3) + (l15 & 3)) : -1;
;         const int j1 = (l31 < 16) ? jsel : -1;
;         const int j2 = (l31 >= 16) ? jsel : -1;
;         const unsigned one_lo = 0x3f80u, one_hi = 0x3f800000u;
; #pragma unroll
;         for (int w = 0; w < 4; ++w) {
;           id1[w] = (j1 == 2 * w) ? one_lo : ((j1 == 2 * w + 1) ? one_hi : 0u);
;           id2[w] = (j2 == 2 * w) ? one_lo : ((j2 == 2 * w + 1) ? one_hi : 0u);
;         }
;       }
;       const bf16x8 B1 = __builtin_bit_cast(bf16x8, id1), B2 = __builtin_bit_cast(bf16x8, id2);
; __device__ __forceinline__ void phase3(const Params& p, unsigned char* smem, unsigned* bar) {
;     ...
;     f32x16 S[4];
; #pragma unroll
;     for (int d = 0; d < 4; ++d)
; #pragma unroll
;       for (int r = 0; r < 16; ++r) S[d][r] = 0.f;
;     scan_chunked(p, smem, blockIdx.x, S, 0, NCH);
.LBB0_311:
	s_andn2_b64 vcc, exec, s[4:5]
	s_cbranch_vccnz .LBB0_320
	v_mov_b32_e32 v152, v218
	s_movk_i32 s4, 0x70
	v_lshlrev_b32_e32 v7, 2, v152
	v_lshlrev_b32_e32 v0, 3, v152
	v_and_b32_e32 v6, 4, v7
	v_and_or_b32 v4, v0, s4, v6
	v_lshrrev_b32_e32 v9, 1, v152
	v_and_b32_e32 v11, 3, v152
	v_bfe_u32 v5, v152, 5, 1
	v_lshl_add_u32 v4, v4, 1, 16
	s_movk_i32 s12, 0x110
	v_and_or_b32 v9, v9, 4, v11
	v_lshrrev_b32_e32 v11, 4, v152
	v_mad_u64_u32 v[158:159], s[10:11], v11, s12, v[4:5]
	v_add_u32_e32 v11, 0x100, v152
	v_lshrrev_b32_e32 v18, 4, v11
	v_mad_u64_u32 v[160:161], s[10:11], v18, s12, v[4:5]
	v_add_u32_e32 v18, 0x200, v152
	v_lshrrev_b32_e32 v18, 4, v18
	v_mad_u64_u32 v[162:163], s[10:11], v18, s12, v[4:5]
	v_add_u32_e32 v18, 0x300, v152
	v_and_b32_e32 v3, 31, v152
	v_and_or_b32 v6, v0, 48, v6
	v_lshl_add_u32 v222, v5, 4, 16
	v_lshrrev_b32_e32 v18, 4, v18
	v_ashrrev_i32_e32 v1, 6, v152
	v_lshl_add_u32 v6, v6, 1, 16
	v_add_u32_e32 v221, 16, v7
	v_mul_u32_u24_e32 v7, 0x110, v3
	v_mad_u32_u24 v223, v3, s12, v222
	v_lshlrev_b32_e32 v8, 7, v3
	v_mad_u64_u32 v[164:165], s[10:11], v18, s12, v[4:5]
	v_lshrrev_b32_e32 v4, 3, v152
	s_movk_i32 s12, 0x90
	v_sub_u32_e32 v224, v223, v8
	v_lshl_or_b32 v8, v1, 5, v3
	v_mad_u64_u32 v[166:167], s[10:11], v4, s12, v[6:7]
	v_lshrrev_b32_e32 v4, 3, v11
	v_lshlrev_b32_e32 v156, 9, v5
	v_add_u32_e32 v10, 0x1000, v8
	v_mad_u64_u32 v[168:169], s[10:11], v4, s12, v[6:7]
	v_or_b32_e32 v4, 0x800, v156
	v_add_u32_e32 v174, v4, v8
	v_add_u32_e32 v176, v4, v10
	v_or_b32_e32 v4, 0x880, v156
	v_lshlrev_b32_e32 v2, 6, v3
	v_add_u32_e32 v178, v4, v8
	v_add_u32_e32 v180, v4, v10
	v_or_b32_e32 v4, 0x900, v156
	v_lshl_or_b32 v154, v1, 11, v2
	v_bfe_u32 v1, v152, 2, 1
	v_add_u32_e32 v182, v4, v8
	v_add_u32_e32 v184, v4, v10
	v_or_b32_e32 v4, 0x980, v156
	v_cmp_eq_u32_e32 vcc, v1, v5
	v_add_u32_e32 v186, v4, v8
	v_add_u32_e32 v188, v4, v10
	v_or_b32_e32 v4, 0xc00, v156
	v_cndmask_b32_e32 v1, -1, v9, vcc
	v_cmp_gt_u32_e32 vcc, 16, v3
	v_add_u32_e32 v190, v4, v8
	v_add_u32_e32 v192, v4, v10
	v_or_b32_e32 v4, 0xc80, v156
	v_cndmask_b32_e32 v9, -1, v1, vcc
	v_cmp_lt_u32_e32 vcc, 15, v3
	v_add_u32_e32 v194, v4, v8
	v_add_u32_e32 v196, v4, v10
	v_or_b32_e32 v4, 0xd00, v156
	v_cndmask_b32_e32 v3, -1, v1, vcc
	v_add_u32_e32 v198, v4, v8
	v_add_u32_e32 v200, v4, v10
	v_or_b32_e32 v4, 0xd80, v156
	v_cmp_eq_u32_e32 vcc, 1, v9
	v_lshlrev_b32_e32 v2, 2, v5
	v_add_u32_e32 v202, v4, v8
	v_add_u32_e32 v204, v4, v10
	v_cndmask_b32_e64 v4, 0, 1.0, vcc
	v_mov_b32_e32 v5, 0x3f80
	v_cmp_ne_u32_e32 vcc, 0, v9
	s_load_dwordx2 s[8:9], s[0:1], 0x90
	s_mov_b32 s7, 0
	v_cndmask_b32_e32 v96, v5, v4, vcc
	v_cmp_eq_u32_e32 vcc, 1, v3
	s_mul_i32 s6, s89, 17
	s_waitcnt lgkmcnt(0)
	s_add_u32 s2, s8, 0x6090000
	v_cndmask_b32_e64 v4, 0, 1.0, vcc
	v_cmp_ne_u32_e32 vcc, 0, v3
	s_addc_u32 s16, s9, 0
	s_add_u32 s17, s8, 0xc5d9000
	v_cndmask_b32_e32 v100, v5, v4, vcc
	v_cmp_eq_u32_e32 vcc, 3, v9
	s_addc_u32 s18, s9, 0
	s_lshl_b64 s[10:11], s[6:7], 2
	v_cndmask_b32_e64 v4, 0, 1.0, vcc
	v_cmp_ne_u32_e32 vcc, 2, v9
	s_add_u32 s6, s8, s10
	v_add_u32_e32 v12, 0x800, v0
	v_cndmask_b32_e32 v97, v5, v4, vcc
	v_cmp_eq_u32_e32 vcc, 3, v3
	v_add_u32_e32 v14, 0x1000, v0
	v_add_u32_e32 v16, 0x1800, v0
	v_cndmask_b32_e64 v4, 0, 1.0, vcc
	v_cmp_ne_u32_e32 vcc, 2, v3
	s_addc_u32 s9, s9, s11
	v_mov_b32_e32 v157, 0
	v_cndmask_b32_e32 v101, v5, v4, vcc
	v_cmp_eq_u32_e32 vcc, 5, v9
	v_ashrrev_i32_e32 v1, 31, v0
	v_ashrrev_i32_e32 v13, 31, v12
	v_cndmask_b32_e64 v4, 0, 1.0, vcc
	v_cmp_ne_u32_e32 vcc, 4, v9
	v_ashrrev_i32_e32 v15, 31, v14
	v_ashrrev_i32_e32 v17, 31, v16
	v_cndmask_b32_e32 v98, v5, v4, vcc
	v_cmp_eq_u32_e32 vcc, 5, v3
	v_add_u32_e32 v170, v156, v8
	v_add_u32_e32 v172, v10, v156
	v_cndmask_b32_e64 v4, 0, 1.0, vcc
	v_cmp_ne_u32_e32 vcc, 4, v3
	s_add_u32 s8, s6, 0xf223840
	v_ashrrev_i32_e32 v11, 31, v10
	v_cndmask_b32_e32 v102, v5, v4, vcc
	v_cmp_eq_u32_e32 vcc, 7, v9
	s_mul_i32 s19, s89, 0x81
	v_ashrrev_i32_e32 v153, 31, v152
	v_cndmask_b32_e64 v4, 0, 1.0, vcc
	v_cmp_ne_u32_e32 vcc, 6, v9
	v_ashrrev_i32_e32 v9, 31, v8
	v_ashrrev_i32_e32 v155, 31, v154
	v_cndmask_b32_e32 v99, v5, v4, vcc
	v_cmp_eq_u32_e32 vcc, 7, v3
	v_cmp_eq_u32_e64 s[4:5], 0, v152
	v_ashrrev_i32_e32 v171, 31, v170
	v_cndmask_b32_e64 v4, 0, 1.0, vcc
	v_cmp_ne_u32_e32 vcc, 6, v3
	v_ashrrev_i32_e32 v173, 31, v172
	v_ashrrev_i32_e32 v175, 31, v174
	v_ashrrev_i32_e32 v177, 31, v176
	v_ashrrev_i32_e32 v179, 31, v178
	v_ashrrev_i32_e32 v181, 31, v180
	v_ashrrev_i32_e32 v183, 31, v182
	v_ashrrev_i32_e32 v185, 31, v184
	v_ashrrev_i32_e32 v187, 31, v186
	v_ashrrev_i32_e32 v189, 31, v188
	v_ashrrev_i32_e32 v191, 31, v190
	v_ashrrev_i32_e32 v193, 31, v192
	v_ashrrev_i32_e32 v195, 31, v194
	v_ashrrev_i32_e32 v197, 31, v196
	v_ashrrev_i32_e32 v199, 31, v198
	v_ashrrev_i32_e32 v201, 31, v200
	v_ashrrev_i32_e32 v203, 31, v202
	v_ashrrev_i32_e32 v205, 31, v204
	v_cndmask_b32_e32 v103, v5, v4, vcc
	s_addc_u32 s9, s9, 0
	v_lshl_add_u64 v[206:207], v[156:157], 0, v[8:9]
	v_lshl_add_u64 v[208:209], v[156:157], 0, v[10:11]
	v_lshlrev_b64 v[210:211], 1, v[0:1]
	v_lshlrev_b64 v[212:213], 1, v[12:13]
	v_lshlrev_b64 v[214:215], 1, v[14:15]
	v_lshlrev_b64 v[216:217], 1, v[16:17]
	s_movk_i32 s6, 0x4000
	v_lshlrev_b32_e32 v156, 1, v2
	s_mov_b64 s[10:11], 0x8000
	s_mov_b32 s20, 0x8000
	v_add_u32_e32 v159, v222, v7
	v_mov_b32_e32 v161, 16
	v_mov_b32_e32 v0, v157
	v_mov_b32_e32 v1, v157
	v_mov_b32_e32 v2, v157
	v_mov_b32_e32 v3, v157
	v_mov_b32_e32 v4, v157
	v_mov_b32_e32 v5, v157
	v_mov_b32_e32 v6, v157
	v_mov_b32_e32 v7, v157
	v_mov_b32_e32 v8, v157
	v_mov_b32_e32 v9, v157
	v_mov_b32_e32 v10, v157
	v_mov_b32_e32 v11, v157
	v_mov_b32_e32 v12, v157
	v_mov_b32_e32 v13, v157
	v_mov_b32_e32 v14, v157
	v_mov_b32_e32 v15, v157
	v_mov_b32_e32 v16, v157
	v_mov_b32_e32 v17, v157
	v_mov_b32_e32 v18, v157
	v_mov_b32_e32 v19, v157
	v_mov_b32_e32 v20, v157
	v_mov_b32_e32 v21, v157
	v_mov_b32_e32 v22, v157
	v_mov_b32_e32 v23, v157
	v_mov_b32_e32 v24, v157
	v_mov_b32_e32 v25, v157
	v_mov_b32_e32 v26, v157
	v_mov_b32_e32 v27, v157
	v_mov_b32_e32 v28, v157
	v_mov_b32_e32 v29, v157
	v_mov_b32_e32 v30, v157
	v_mov_b32_e32 v31, v157
	v_mov_b32_e32 v32, v157
	v_mov_b32_e32 v33, v157
	v_mov_b32_e32 v34, v157
	v_mov_b32_e32 v35, v157
	v_mov_b32_e32 v36, v157
	v_mov_b32_e32 v37, v157
	v_mov_b32_e32 v38, v157
	v_mov_b32_e32 v39, v157
	v_mov_b32_e32 v40, v157
	v_mov_b32_e32 v41, v157
	v_mov_b32_e32 v42, v157
	v_mov_b32_e32 v43, v157
	v_mov_b32_e32 v44, v157
	v_mov_b32_e32 v45, v157
	v_mov_b32_e32 v46, v157
	v_mov_b32_e32 v47, v157
	v_mov_b32_e32 v48, v157
	v_mov_b32_e32 v49, v157
	v_mov_b32_e32 v50, v157
	v_mov_b32_e32 v51, v157
	v_mov_b32_e32 v52, v157
	v_mov_b32_e32 v53, v157
	v_mov_b32_e32 v54, v157
	v_mov_b32_e32 v55, v157
	v_mov_b32_e32 v56, v157
	v_mov_b32_e32 v57, v157
	v_mov_b32_e32 v58, v157
	v_mov_b32_e32 v59, v157
	v_mov_b32_e32 v60, v157
	v_mov_b32_e32 v61, v157
	v_mov_b32_e32 v62, v157
	v_mov_b32_e32 v63, v157
	v_mov_b32_e32 v225, 0
	s_setprio 3
	s_branch .LBB0_316

; __device__ __forceinline__ void scan_chunked(const Params& p, unsigned char* smem, int bh, f32x16 (&S)[4], const int c_begin, const int c_end) {
;     ...
;     {
;       const u16* Xq = DX + ((size_t)(bh * NCH + c) * 3) * 8192; const u16* Xk = Xq + 8192; const u16* Xv = Xk + 8192;
;       const u16* Tg = TA + (size_t)(bh * NCH + c) * 8704; const u16* Ag = Tg + 4096;
; #pragma unroll
;       for (int i = 0; i < 4; ++i) { pk[i] = *(const u32x4*)(Xk + (tid + 256 * i) * 8); pq[i] = *(const u32x4*)(Xq + (tid + 256 * i) * 8); }
; #pragma unroll
;       for (int i = 0; i < 2; ++i) { pT[i] = *(const u32x4*)(Tg + (tid + 256 * i) * 8); pA[i] = *(const u32x4*)(Ag + (tid + 256 * i) * 8); }
;       psc = ((const float*)(Tg + 8192))[tid];
; #pragma unroll
;       for (int i = 0; i < 8; ++i) pv[i] = *(const uint2*)(Xv + (wave * 32 + l31) * 64 + 32 * (i >> 2) + 8 * (i & 3) + 4 * hf);
;     }
; #pragma unroll
;     for (int i = 0; i < 4; ++i) {
;       int idx = tid + 256 * i; int row = idx >> 4, ch = idx & 15; const int po = (ch >> 1) * 16 + (ch & 1) * 4;
;       u16* dk = sk + row * 136 + po; *(uint2*)dk = make_uint2(pk[i].x, pk[i].y); *(uint2*)(dk + 8) = make_uint2(pk[i].z, pk[i].w);
;       u16* dq = sq + row * 136 + po; *(uint2*)dq = make_uint2(pq[i].x, pq[i].y); *(uint2*)(dq + 8) = make_uint2(pq[i].z, pq[i].w);
;     }
; #pragma unroll
;     for (int i = 0; i < 2; ++i) {
;       int idx = tid + 256 * i; int row = idx >> 3, ch = idx & 7; const int po = (ch >> 1) * 16 + (ch & 1) * 4;
;       u16* dt = sT + row * 72 + po; *(uint2*)dt = make_uint2(pT[i].x, pT[i].y); *(uint2*)(dt + 8) = make_uint2(pT[i].z, pT[i].w);
;       u16* da = sA + row * 72 + po; *(uint2*)da = make_uint2(pA[i].x, pA[i].y); *(uint2*)(da + 8) = make_uint2(pA[i].z, pA[i].w);
;     }
;     sSC[tid] = psc;
;     lds_barrier();
;     __builtin_amdgcn_sched_barrier(0);
;     u32x4 yf[4];
;     {
;       f32x16 x0, x1;
; #pragma unroll
;       for (int r = 0; r < 16; ++r) { x0[r] = 0.f; x1[r] = 0.f; }
; #pragma unroll
;       for (int dt = 0; dt < 4; ++dt)
; #pragma unroll
;         for (int s = 0; s < 2; ++s) {
;           u32x4 sb = {cvtpk(S[dt][8 * s + 0], S[dt][8 * s + 1]), cvtpk(S[dt][8 * s + 2], S[dt][8 * s + 3]), cvtpk(S[dt][8 * s + 4], S[dt][8 * s + 5]), cvtpk(S[dt][8 * s + 6], S[dt][8 * s + 7])};
;           const bf16x8 k0f = *(const bf16x8*)(sk + (l31) * 136 + 32 * dt + 16 * s + 8 * hf);
.LBB0_315:
	s_add_i32 s21, s7, s19
	s_mul_i32 s12, s21, 0xc000
	s_mul_hi_u32 s13, s21, 0xc000
	s_add_u32 s12, s2, s12
	s_addc_u32 s13, s16, s13
	s_add_u32 s14, s12, 0x4000
	s_addc_u32 s15, s13, 0
	s_mul_hi_u32 s23, s21, 0x4400
	s_mulk_i32 s21, 0x4400
	s_add_u32 s22, s17, s21
	s_addc_u32 s23, s18, s23
	v_lshl_add_u64 v[64:65], s[14:15], 0, v[210:211]
	v_lshl_add_u64 v[72:73], s[14:15], 0, v[212:213]
	v_lshl_add_u64 v[80:81], s[14:15], 0, v[214:215]
	v_lshl_add_u64 v[88:89], s[14:15], 0, v[216:217]
	s_add_u32 s14, s22, 0x2000
	v_lshl_add_u64 v[68:69], s[12:13], 0, v[210:211]
	v_lshl_add_u64 v[76:77], s[12:13], 0, v[212:213]
	v_lshl_add_u64 v[84:85], s[12:13], 0, v[214:215]
	v_lshl_add_u64 v[92:93], s[12:13], 0, v[216:217]
	s_addc_u32 s15, s23, 0
	v_lshl_add_u64 v[104:105], s[22:23], 0, v[210:211]
	global_load_dwordx4 v[64:67], v[64:65], off
	s_nop 0
	global_load_dwordx4 v[68:71], v[68:69], off
	s_nop 0
	global_load_dwordx4 v[72:75], v[72:73], off
	s_nop 0
	global_load_dwordx4 v[76:79], v[76:77], off
	s_nop 0
	global_load_dwordx4 v[80:83], v[80:81], off
	s_nop 0
	global_load_dwordx4 v[84:87], v[84:85], off
	s_nop 0
	global_load_dwordx4 v[88:91], v[88:89], off
	s_nop 0
	global_load_dwordx4 v[92:95], v[92:93], off
	v_lshl_add_u64 v[106:107], s[14:15], 0, v[210:211]
	global_load_dwordx4 v[120:123], v[104:105], off
	global_load_dwordx4 v[124:127], v[106:107], off
	v_lshl_add_u64 v[104:105], s[22:23], 0, v[212:213]
	v_lshl_add_u64 v[106:107], s[14:15], 0, v[212:213]
	global_load_dwordx4 v[128:131], v[104:105], off
	global_load_dwordx4 v[132:135], v[106:107], off
	v_lshl_add_u64 v[104:105], v[152:153], 2, s[22:23]
	v_add_co_u32_e32 v104, vcc, s6, v104
	v_add_u32_e32 v137, 0x4000, v158
	s_nop 0
	v_addc_co_u32_e32 v105, vcc, 0, v105, vcc
	global_load_dword v136, v[104:105], off
	v_lshl_add_u64 v[104:105], v[154:155], 1, s[12:13]
	v_lshl_add_u64 v[104:105], v[104:105], 0, v[156:157]
	v_lshl_add_u64 v[106:107], v[104:105], 0, s[10:11]
	v_add_co_u32_e32 v104, vcc, s20, v104
	v_add_u32_e32 v138, 0x4000, v160
	s_nop 0
	v_addc_co_u32_e32 v105, vcc, 0, v105, vcc
	global_load_dwordx2 v[118:119], v[104:105], off
	global_load_dwordx2 v[116:117], v[106:107], off offset:64
	global_load_dwordx2 v[112:113], v[106:107], off offset:80
	global_load_dwordx2 v[108:109], v[106:107], off offset:96
	s_nop 0
	global_load_dwordx2 v[104:105], v[106:107], off offset:112
	global_load_dwordx2 v[114:115], v[106:107], off offset:16
	global_load_dwordx2 v[110:111], v[106:107], off offset:32
	s_nop 0
	global_load_dwordx2 v[106:107], v[106:107], off offset:48
	v_add_u32_e32 v139, 0x4000, v162
	v_add_u32_e32 v140, 0x4000, v164
	v_add_u32_e32 v141, 0x8800, v166
	v_add_u32_e32 v142, 0xa800, v166
	v_add_u32_e32 v143, 0x8800, v168
	v_add_u32_e32 v144, 0xa800, v168
	s_waitcnt vmcnt(20)
	ds_write2_b64 v158, v[64:65], v[66:67] offset1:2
	s_waitcnt vmcnt(19)
	ds_write2_b64 v137, v[68:69], v[70:71] offset0:128 offset1:130
	s_waitcnt vmcnt(18)
	ds_write2_b64 v160, v[72:73], v[74:75] offset1:2
	s_waitcnt vmcnt(17)
	ds_write2_b64 v138, v[76:77], v[78:79] offset0:128 offset1:130
	s_waitcnt vmcnt(16)
	ds_write2_b64 v162, v[80:81], v[82:83] offset1:2
	s_waitcnt vmcnt(15)
	ds_write2_b64 v139, v[84:85], v[86:87] offset0:128 offset1:130
	s_waitcnt vmcnt(14)
	ds_write2_b64 v164, v[88:89], v[90:91] offset1:2
	s_waitcnt vmcnt(13)
	ds_write2_b64 v140, v[92:93], v[94:95] offset0:128 offset1:130
	s_waitcnt vmcnt(12)
	ds_write2_b64 v141, v[120:121], v[122:123] offset1:2
	s_waitcnt vmcnt(11)
	ds_write2_b64 v142, v[124:125], v[126:127] offset0:128 offset1:130
	s_waitcnt vmcnt(10)
	ds_write2_b64 v143, v[128:129], v[130:131] offset1:2
	s_waitcnt vmcnt(9)
	ds_write2_b64 v144, v[132:133], v[134:135] offset0:128 offset1:130
	s_waitcnt vmcnt(8)
	ds_write_b32 v221, v136 offset:53248
	s_waitcnt lgkmcnt(0)
	s_barrier
	ds_read_b128 v[64:67], v223
	ds_read_b128 v[128:131], v223 offset:32
	v_cvt_pk_bf16_f32 v120, v48, v49
	v_cvt_pk_bf16_f32 v121, v50, v51
	v_cvt_pk_bf16_f32 v122, v52, v53
	v_cvt_pk_bf16_f32 v123, v54, v55
	ds_read_b128 v[80:83], v223 offset:8704
	ds_read_b128 v[132:135], v223 offset:8736
	v_cvt_pk_bf16_f32 v124, v56, v57
	v_cvt_pk_bf16_f32 v125, v58, v59
	s_waitcnt lgkmcnt(3)
	v_mfma_f32_32x32x16_bf16 v[64:79], v[64:67], v[120:123], 0
	v_cvt_pk_bf16_f32 v126, v60, v61
	v_cvt_pk_bf16_f32 v127, v62, v63
	v_cvt_pk_bf16_f32 v136, v40, v41
	v_cvt_pk_bf16_f32 v137, v42, v43
	v_cvt_pk_bf16_f32 v138, v44, v45
	v_cvt_pk_bf16_f32 v139, v46, v47
	v_cvt_pk_bf16_f32 v148, v24, v25
	s_waitcnt lgkmcnt(1)
	v_mfma_f32_32x32x16_bf16 v[80:95], v[80:83], v[120:123], 0
	ds_read_b128 v[140:143], v223 offset:96
	v_cvt_pk_bf16_f32 v149, v26, v27
	v_cvt_pk_bf16_f32 v150, v28, v29
	v_cvt_pk_bf16_f32 v151, v30, v31
	s_waitcnt vmcnt(7)
	v_lshlrev_b32_e32 v163, 16, v118
	v_and_b32_e32 v118, 0xffff0000, v118
	v_mfma_f32_32x32x16_bf16 v[64:79], v[128:131], v[124:127], v[64:79]
	ds_read_b128 v[128:131], v223 offset:64
	s_waitcnt lgkmcnt(2)
	v_mfma_f32_32x32x16_bf16 v[80:95], v[132:135], v[124:127], v[80:95]
	v_cvt_pk_bf16_f32 v132, v32, v33
	v_cvt_pk_bf16_f32 v133, v34, v35
	v_cvt_pk_bf16_f32 v134, v36, v37
	v_cvt_pk_bf16_f32 v135, v38, v39
	s_waitcnt lgkmcnt(0)
	s_nop 0
	v_mfma_f32_32x32x16_bf16 v[64:79], v[128:131], v[132:135], v[64:79]
	ds_read_b128 v[128:131], v223 offset:8768
	ds_read_b128 v[144:147], v223 offset:8800
	s_waitcnt lgkmcnt(1)
	v_mfma_f32_32x32x16_bf16 v[80:95], v[128:131], v[132:135], v[80:95]
	ds_read_b128 v[128:131], v223 offset:128
	v_mfma_f32_32x32x16_bf16 v[64:79], v[140:143], v[136:139], v[64:79]
	v_cvt_pk_bf16_f32 v140, v16, v17
	v_cvt_pk_bf16_f32 v141, v18, v19
	v_cvt_pk_bf16_f32 v142, v20, v21
	v_cvt_pk_bf16_f32 v143, v22, v23
	s_waitcnt lgkmcnt(1)
; __device__ __forceinline__ unsigned cvtpk(float lo, float hi) { f32x2_t v = {lo, hi}; bf16x2_t b = __builtin_convertvector(v, bf16x2_t); return __builtin_bit_cast(unsigned, b); }
; __device__ __forceinline__ float bflo(unsigned v) { return __uint_as_float(v << 16); }
; __device__ __forceinline__ float bfhi(unsigned v) { return __uint_as_float(v & 0xffff0000u); }
; __device__ __forceinline__ void scan_chunked(const Params& p, unsigned char* smem, int bh, f32x16 (&S)[4], const int c_begin, const int c_end) {
;     ...
;     if (c >= P2_SPLIT && (c & 7) == 0) {
;       const unsigned need = (c == 128) ? 1u : 8u;
;       if (tid == 0) {
;         const unsigned* f = (const unsigned*)(p.ws + OFF_BAR) + 16 + bh * 17 + (c >> 3);
;         while (__hip_atomic_load(f, __ATOMIC_RELAXED, __HIP_MEMORY_SCOPE_AGENT) < need) __builtin_amdgcn_s_sleep(2);
;         __builtin_amdgcn_fence(__ATOMIC_ACQUIRE, "agent");
;     ...
; #pragma unroll
;       for (int g = 0; g < 4; ++g) {
;         {
;           float4 bg4 = *(const float4*)(sSC + 64 + 8 * g + 4 * hf);
;           uint2 vb = pv[g];
;           yf[(g >> 1)][(g & 1) * 2 + 0] = cvtpk(bflo(vb.x) - bg4.x * x0[4 * g + 0], bfhi(vb.x) - bg4.y * x0[4 * g + 1]);
;           yf[(g >> 1)][(g & 1) * 2 + 1] = cvtpk(bflo(vb.y) - bg4.z * x0[4 * g + 2], bfhi(vb.y) - bg4.w * x0[4 * g + 3]);
;         }
;         {
;           float4 bg4 = *(const float4*)(sSC + 64 + 32 + 8 * g + 4 * hf);
;           uint2 vb = pv[4 + g];
;           yf[2 + (g >> 1)][(g & 1) * 2 + 0] = cvtpk(bflo(vb.x) - bg4.x * x1[4 * g + 0], bfhi(vb.x) - bg4.y * x1[4 * g + 1]);
;           yf[2 + (g >> 1)][(g & 1) * 2 + 1] = cvtpk(bflo(vb.y) - bg4.z * x1[4 * g + 2], bfhi(vb.y) - bg4.w * x1[4 * g + 3]);
;         }
;       }
;     }
;     __builtin_amdgcn_sched_barrier(0);
;     u32x4 vnf[4];
;     {
;       f32x16 v0, v1;
; #pragma unroll
;       for (int r = 0; r < 16; ++r) { v0[r] = 0.f; v1[r] = 0.f; }
; #pragma unroll
;       for (int s = 0; s < 4; ++s) {
;         const bf16x8 t0f = *(const bf16x8*)(sT + (l31) * 72 + 16 * s + 8 * hf);
;         const bf16x8 t1f = *(const bf16x8*)(sT + (32 + l31) * 72 + 16 * s + 8 * hf);
;         v0 = mfma32(t0f, __builtin_bit_cast(bf16x8, yf[s]), v0);
;         v1 = mfma32(t1f, __builtin_bit_cast(bf16x8, yf[s]), v1);
;       }
	v_mfma_f32_32x32x16_bf16 v[80:95], v[144:147], v[136:139], v[80:95]
	ds_read_b128 v[144:147], v223 offset:160
	s_waitcnt lgkmcnt(1)
	v_mfma_f32_32x32x16_bf16 v[64:79], v[128:131], v[140:143], v[64:79]
	ds_read_b128 v[128:131], v223 offset:8832
	ds_read_b128 v[226:229], v223 offset:8864
	s_waitcnt lgkmcnt(1)
	v_mfma_f32_32x32x16_bf16 v[80:95], v[128:131], v[140:143], v[80:95]
	ds_read_b128 v[128:131], v223 offset:192
	v_mfma_f32_32x32x16_bf16 v[64:79], v[144:147], v[148:151], v[64:79]
	v_cvt_pk_bf16_f32 v144, v0, v1
	v_cvt_pk_bf16_f32 v145, v2, v3
	v_cvt_pk_bf16_f32 v146, v4, v5
	v_cvt_pk_bf16_f32 v147, v6, v7
	s_waitcnt lgkmcnt(1)
	v_mfma_f32_32x32x16_bf16 v[80:95], v[226:229], v[148:151], v[80:95]
	ds_read_b128 v[226:229], v223 offset:224
	ds_read_b128 v[230:233], v223 offset:8896
	ds_read_b128 v[234:237], v223 offset:8928
	ds_read_b128 v[238:241], v222 offset:53504
	s_waitcnt lgkmcnt(4)
	v_mfma_f32_32x32x16_bf16 v[64:79], v[128:131], v[144:147], v[64:79]
	v_cvt_pk_bf16_f32 v128, v8, v9
	v_cvt_pk_bf16_f32 v129, v10, v11
	v_cvt_pk_bf16_f32 v130, v12, v13
	v_cvt_pk_bf16_f32 v131, v14, v15
	s_waitcnt lgkmcnt(2)
	v_mfma_f32_32x32x16_bf16 v[80:95], v[230:233], v[144:147], v[80:95]
	v_mfma_f32_32x32x16_bf16 v[64:79], v[226:229], v[128:131], v[64:79]
	ds_read_b128 v[226:229], v222 offset:53536
	s_waitcnt lgkmcnt(2)
	v_mfma_f32_32x32x16_bf16 v[80:95], v[234:237], v[128:131], v[80:95]
	s_waitcnt lgkmcnt(1)
	s_nop 7
	v_fma_f32 v64, -v64, v238, v163
	v_fma_f32 v65, -v65, v239, v118
	v_cvt_pk_bf16_f32 v238, v64, v65
	v_lshlrev_b32_e32 v64, 16, v119
	v_and_b32_e32 v65, 0xffff0000, v119
	v_fma_f32 v64, -v66, v240, v64
	v_fma_f32 v65, -v67, v241, v65
	v_cvt_pk_bf16_f32 v239, v64, v65
	ds_read_b128 v[64:67], v222 offset:53632
	ds_read_b128 v[230:233], v222 offset:53664
	s_waitcnt vmcnt(6)
	v_lshlrev_b32_e32 v118, 16, v116
	s_waitcnt lgkmcnt(1)
	v_fma_f32 v64, -v80, v64, v118
	v_and_b32_e32 v80, 0xffff0000, v116
	v_fma_f32 v65, -v81, v65, v80
	v_cvt_pk_bf16_f32 v116, v64, v65
	v_lshlrev_b32_e32 v64, 16, v117
	v_and_b32_e32 v65, 0xffff0000, v117
	v_fma_f32 v64, -v82, v66, v64
	v_fma_f32 v65, -v83, v67, v65
	v_cvt_pk_bf16_f32 v117, v64, v65
	s_waitcnt vmcnt(2)
	v_lshlrev_b32_e32 v64, 16, v114
	v_and_b32_e32 v65, 0xffff0000, v114
	v_fma_f32 v64, -v68, v226, v64
	v_fma_f32 v65, -v69, v227, v65
	v_cvt_pk_bf16_f32 v240, v64, v65
	v_lshlrev_b32_e32 v64, 16, v115
	v_and_b32_e32 v65, 0xffff0000, v115
	v_fma_f32 v64, -v70, v228, v64
	v_fma_f32 v65, -v71, v229, v65
	v_cvt_pk_bf16_f32 v241, v64, v65
	v_lshlrev_b32_e32 v64, 16, v112
	v_and_b32_e32 v65, 0xffff0000, v112
	s_waitcnt lgkmcnt(0)
	v_fma_f32 v64, -v84, v230, v64
	v_fma_f32 v65, -v85, v231, v65
	v_cvt_pk_bf16_f32 v118, v64, v65
	v_lshlrev_b32_e32 v64, 16, v113
	v_fma_f32 v68, -v86, v232, v64
	ds_read_b128 v[64:67], v222 offset:53568
	v_and_b32_e32 v69, 0xffff0000, v113
	v_fma_f32 v69, -v87, v233, v69
	s_waitcnt vmcnt(1)
	v_lshlrev_b32_e32 v80, 16, v110
	v_cvt_pk_bf16_f32 v119, v68, v69
	ds_read_b128 v[68:71], v222 offset:53600
	s_waitcnt lgkmcnt(1)
	v_fma_f32 v64, -v72, v64, v80
	ds_read_b128 v[80:83], v222 offset:53696
	v_and_b32_e32 v72, 0xffff0000, v110
	v_fma_f32 v65, -v73, v65, v72
	v_cvt_pk_bf16_f32 v110, v64, v65
	v_lshlrev_b32_e32 v64, 16, v111
	v_and_b32_e32 v65, 0xffff0000, v111
	v_fma_f32 v64, -v74, v66, v64
	v_fma_f32 v65, -v75, v67, v65
	v_lshlrev_b32_e32 v72, 16, v108
	v_and_b32_e32 v73, 0xffff0000, v108
	v_cvt_pk_bf16_f32 v111, v64, v65
	ds_read_b128 v[64:67], v222 offset:53728
	s_waitcnt lgkmcnt(1)
	v_fma_f32 v72, -v88, v80, v72
	v_fma_f32 v73, -v89, v81, v73
	v_cvt_pk_bf16_f32 v226, v72, v73
	v_lshlrev_b32_e32 v72, 16, v109
	v_and_b32_e32 v73, 0xffff0000, v109
	v_fma_f32 v72, -v90, v82, v72
	v_fma_f32 v73, -v91, v83, v73
	v_cvt_pk_bf16_f32 v227, v72, v73
	s_waitcnt vmcnt(0)
	s_lshr_b32 s14, s7, 3
	s_lshl_b32 s14, s14, 2
	s_add_u32 s14, s8, s14
	s_addc_u32 s15, s9, 0
	global_load_dword v225, v157, s[14:15] offset:4 sc1
	v_lshlrev_b32_e32 v72, 16, v106
	v_fma_f32 v68, -v76, v68, v72
	v_and_b32_e32 v72, 0xffff0000, v106
	v_fma_f32 v69, -v77, v69, v72
	v_cvt_pk_bf16_f32 v112, v68, v69
	v_lshlrev_b32_e32 v68, 16, v107
	v_and_b32_e32 v69, 0xffff0000, v107
	v_fma_f32 v68, -v78, v70, v68
	v_fma_f32 v69, -v79, v71, v69
	v_cvt_pk_bf16_f32 v113, v68, v69
	v_lshlrev_b32_e32 v68, 16, v104
	s_waitcnt lgkmcnt(0)
	v_fma_f32 v64, -v92, v64, v68
	v_and_b32_e32 v68, 0xffff0000, v104
	v_fma_f32 v65, -v93, v65, v68
	v_cvt_pk_bf16_f32 v228, v64, v65
	v_lshlrev_b32_e32 v64, 16, v105
	v_and_b32_e32 v65, 0xffff0000, v105
	v_fma_f32 v64, -v94, v66, v64
	v_fma_f32 v65, -v95, v67, v65
	v_cvt_pk_bf16_f32 v229, v64, v65
	ds_read_b128 v[64:67], v224 offset:34816
	ds_read_b128 v[104:107], v224 offset:34848
	ds_read_b128 v[80:83], v224 offset:39424
	ds_read_b128 v[230:233], v224 offset:39456
	s_waitcnt lgkmcnt(3)
	v_mfma_f32_32x32x16_bf16 v[64:79], v[64:67], v[238:241], 0
	s_waitcnt lgkmcnt(1)
	v_mfma_f32_32x32x16_bf16 v[80:95], v[80:83], v[238:241], 0
	v_mfma_f32_32x32x16_bf16 v[64:79], v[104:107], v[110:113], v[64:79]
	s_waitcnt lgkmcnt(0)
	v_mfma_f32_32x32x16_bf16 v[80:95], v[230:233], v[110:113], v[80:95]
	ds_read_b128 v[104:107], v224 offset:34880
	ds_read_b128 v[108:111], v224 offset:34912
	s_waitcnt lgkmcnt(1)
	v_mfma_f32_32x32x16_bf16 v[64:79], v[104:107], v[116:119], v[64:79]
	ds_read_b128 v[104:107], v224 offset:39488
	ds_read_b128 v[112:115], v224 offset:39520
	s_waitcnt lgkmcnt(1)
	v_mfma_f32_32x32x16_bf16 v[80:95], v[104:107], v[116:119], v[80:95]
	v_mfma_f32_32x32x16_bf16 v[64:79], v[108:111], v[226:229], v[64:79]
	s_waitcnt lgkmcnt(0)
; __device__ __forceinline__ unsigned cvtpk(float lo, float hi) { f32x2_t v = {lo, hi}; bf16x2_t b = __builtin_convertvector(v, bf16x2_t); return __builtin_bit_cast(unsigned, b); }
; __device__ __forceinline__ void scan_chunked(const Params& p, unsigned char* smem, int bh, f32x16 (&S)[4], const int c_begin, const int c_end) {
;     ...
; #pragma unroll
;       for (int g = 0; g < 4; ++g) {
;         vnf[(g >> 1)][(g & 1) * 2 + 0] = cvtpk(v0[4 * g + 0], v0[4 * g + 1]);
;         vnf[(g >> 1)][(g & 1) * 2 + 1] = cvtpk(v0[4 * g + 2], v0[4 * g + 3]);
;         vnf[2 + (g >> 1)][(g & 1) * 2 + 0] = cvtpk(v1[4 * g + 0], v1[4 * g + 1]);
;         vnf[2 + (g >> 1)][(g & 1) * 2 + 1] = cvtpk(v1[4 * g + 2], v1[4 * g + 3]);
;       }
;     }
;     __builtin_amdgcn_sched_barrier(0);
;     u16* Oq = DX + ((size_t)(bh * NCH + c) * 3) * 8192;
;     {
;       f32x16 o0, o1;
; #pragma unroll
;       for (int r = 0; r < 16; ++r) { o0[r] = 0.f; o1[r] = 0.f; }
; #pragma unroll
;       for (int dt = 0; dt < 4; ++dt)
; #pragma unroll
;         for (int s = 0; s < 2; ++s) {
;           u32x4 sb = {cvtpk(S[dt][8 * s + 0], S[dt][8 * s + 1]), cvtpk(S[dt][8 * s + 2], S[dt][8 * s + 3]), cvtpk(S[dt][8 * s + 4], S[dt][8 * s + 5]), cvtpk(S[dt][8 * s + 6], S[dt][8 * s + 7])};
;           const bf16x8 q0f = *(const bf16x8*)(sq + (l31) * 136 + 32 * dt + 16 * s + 8 * hf);
;           const bf16x8 q1f = *(const bf16x8*)(sq + (32 + l31) * 136 + 32 * dt + 16 * s + 8 * hf);
;           o0 = mfma32(q0f, __builtin_bit_cast(bf16x8, sb), o0);
;           o1 = mfma32(q1f, __builtin_bit_cast(bf16x8, sb), o1);
;         }
; #pragma unroll
;       for (int g = 0; g < 4; ++g) {
;         float4 e0 = *(const float4*)(sSC + 128 + 8 * g + 4 * hf), e1 = *(const float4*)(sSC + 128 + 32 + 8 * g + 4 * hf);
;         o0[4 * g + 0] *= e0.x; o0[4 * g + 1] *= e0.y; o0[4 * g + 2] *= e0.z; o0[4 * g + 3] *= e0.w;
;         o1[4 * g + 0] *= e1.x; o1[4 * g + 1] *= e1.y; o1[4 * g + 2] *= e1.z; o1[4 * g + 3] *= e1.w;
;       }
; #pragma unroll
;       for (int s = 0; s < 4; ++s) {
;         const bf16x8 a0f = *(const bf16x8*)(sA + (l31) * 72 + 16 * s + 8 * hf);
;         const bf16x8 a1f = *(const bf16x8*)(sA + (32 + l31) * 72 + 16 * s + 8 * hf);
;         o0 = mfma32(a0f, __builtin_bit_cast(bf16x8, vnf[s]), o0);
;         o1 = mfma32(a1f, __builtin_bit_cast(bf16x8, vnf[s]), o1);
;       }
	v_mfma_f32_32x32x16_bf16 v[80:95], v[112:115], v[226:229], v[80:95]
	s_nop 9
	v_cvt_pk_bf16_f32 v116, v64, v65
	v_cvt_pk_bf16_f32 v117, v66, v67
	v_cvt_pk_bf16_f32 v118, v68, v69
	v_cvt_pk_bf16_f32 v119, v70, v71
	v_cvt_pk_bf16_f32 v112, v72, v73
	v_cvt_pk_bf16_f32 v113, v74, v75
	v_cvt_pk_bf16_f32 v114, v76, v77
	v_cvt_pk_bf16_f32 v108, v80, v81
	v_cvt_pk_bf16_f32 v109, v82, v83
	v_cvt_pk_bf16_f32 v110, v84, v85
	v_cvt_pk_bf16_f32 v111, v86, v87
	v_cvt_pk_bf16_f32 v104, v88, v89
	v_cvt_pk_bf16_f32 v105, v90, v91
	v_cvt_pk_bf16_f32 v115, v78, v79
	v_cvt_pk_bf16_f32 v106, v92, v93
	v_cvt_pk_bf16_f32 v107, v94, v95
	ds_read_b128 v[64:67], v223 offset:17408
	ds_read_b128 v[226:229], v223 offset:17440
	ds_read_b128 v[80:83], v223 offset:26112
	ds_read_b128 v[230:233], v223 offset:26144
	s_waitcnt lgkmcnt(3)
	v_mfma_f32_32x32x16_bf16 v[64:79], v[64:67], v[120:123], 0
	s_waitcnt lgkmcnt(1)
	v_mfma_f32_32x32x16_bf16 v[80:95], v[80:83], v[120:123], 0
	v_mfma_f32_32x32x16_bf16 v[64:79], v[226:229], v[124:127], v[64:79]
	s_waitcnt lgkmcnt(0)
	v_mfma_f32_32x32x16_bf16 v[80:95], v[230:233], v[124:127], v[80:95]
	ds_read_b128 v[120:123], v223 offset:17472
	ds_read_b128 v[124:127], v223 offset:17504
	s_waitcnt lgkmcnt(1)
	v_mfma_f32_32x32x16_bf16 v[64:79], v[120:123], v[132:135], v[64:79]
	ds_read_b128 v[120:123], v223 offset:26176
	ds_read_b128 v[226:229], v223 offset:26208
	s_waitcnt lgkmcnt(1)
	v_mfma_f32_32x32x16_bf16 v[80:95], v[120:123], v[132:135], v[80:95]
	v_mfma_f32_32x32x16_bf16 v[64:79], v[124:127], v[136:139], v[64:79]
	ds_read_b128 v[120:123], v223 offset:17536
	ds_read_b128 v[124:127], v223 offset:17568
	s_waitcnt lgkmcnt(2)
	v_mfma_f32_32x32x16_bf16 v[80:95], v[226:229], v[136:139], v[80:95]
	s_waitcnt lgkmcnt(1)
	v_mfma_f32_32x32x16_bf16 v[64:79], v[120:123], v[140:143], v[64:79]
	ds_read_b128 v[120:123], v223 offset:26240
	ds_read_b128 v[132:135], v223 offset:26272
	s_waitcnt lgkmcnt(1)
	v_mfma_f32_32x32x16_bf16 v[80:95], v[120:123], v[140:143], v[80:95]
	v_mfma_f32_32x32x16_bf16 v[64:79], v[124:127], v[148:151], v[64:79]
	ds_read_b128 v[120:123], v223 offset:17600
	ds_read_b128 v[124:127], v223 offset:17632
	s_waitcnt lgkmcnt(2)
	v_mfma_f32_32x32x16_bf16 v[80:95], v[132:135], v[148:151], v[80:95]
	s_waitcnt lgkmcnt(1)
	v_mfma_f32_32x32x16_bf16 v[64:79], v[120:123], v[144:147], v[64:79]
	ds_read_b128 v[120:123], v223 offset:26304
	ds_read_b128 v[132:135], v223 offset:26336
	s_waitcnt lgkmcnt(1)
	v_mfma_f32_32x32x16_bf16 v[80:95], v[120:123], v[144:147], v[80:95]
	v_mfma_f32_32x32x16_bf16 v[64:79], v[124:127], v[128:131], v[64:79]
	ds_read_b128 v[124:127], v222 offset:53824
	ds_read_b128 v[136:139], v222 offset:53856
	ds_read_b128 v[140:143], v222 offset:53760
	ds_read_b128 v[148:151], v222 offset:53792
	ds_read_b128 v[226:229], v222 offset:53888
	ds_read_b128 v[230:233], v222 offset:53920
	s_waitcnt lgkmcnt(4)
	s_nop 4
	v_pk_mul_f32 v[78:79], v[78:79], v[138:139]
	v_mfma_f32_32x32x16_bf16 v[80:95], v[132:135], v[128:131], v[80:95]
	v_mul_f32_e64 v76, v76, v136
	v_mul_f32_e64 v77, v77, v137
	v_mul_f32_e64 v74, v74, v126
	v_mul_f32_e64 v75, v75, v127
	v_mul_f32_e64 v72, v72, v124
	v_mul_f32_e64 v73, v73, v125
	ds_read_b128 v[120:123], v222 offset:53952
	ds_read_b128 v[124:127], v222 offset:53984
	ds_read_b128 v[136:139], v224 offset:44032
	s_waitcnt lgkmcnt(5)
	v_pk_mul_f32 v[70:71], v[70:71], v[150:151]
	v_pk_mul_f32 v[68:69], v[68:69], v[148:149]
	v_pk_mul_f32 v[66:67], v[66:67], v[142:143]
	v_pk_mul_f32 v[64:65], v[64:65], v[140:141]
	s_waitcnt lgkmcnt(1)
	v_pk_mul_f32 v[94:95], v[94:95], v[126:127]
	v_pk_mul_f32 v[92:93], v[92:93], v[124:125]
	ds_read_b128 v[124:127], v224 offset:48640
	ds_read_b128 v[128:131], v224 offset:44064
	s_waitcnt lgkmcnt(2)
	v_mfma_f32_32x32x16_bf16 v[64:79], v[136:139], v[116:119], v[64:79]
	v_mul_f32_e64 v90, v90, v122
	v_mul_f32_e64 v91, v91, v123
	v_mul_f32_e64 v88, v88, v120
	v_mul_f32_e64 v89, v89, v121
	v_mul_f32_e64 v86, v86, v232
	v_mul_f32_e64 v87, v87, v233
	v_pk_mul_f32 v[84:85], v[84:85], v[230:231]
	v_pk_mul_f32 v[82:83], v[82:83], v[228:229]
	v_pk_mul_f32 v[80:81], v[80:81], v[226:227]
	ds_read_b128 v[120:123], v224 offset:48672
	s_waitcnt lgkmcnt(1)
	v_mfma_f32_32x32x16_bf16 v[64:79], v[128:131], v[112:115], v[64:79]
	v_mfma_f32_32x32x16_bf16 v[80:95], v[124:127], v[116:119], v[80:95]
	s_waitcnt lgkmcnt(0)
	v_mfma_f32_32x32x16_bf16 v[80:95], v[120:123], v[112:115], v[80:95]
	ds_read_b128 v[120:123], v224 offset:44096
	ds_read_b128 v[124:127], v224 offset:44128
	s_waitcnt lgkmcnt(1)
	v_mfma_f32_32x32x16_bf16 v[64:79], v[120:123], v[108:111], v[64:79]
	ds_read_b128 v[120:123], v224 offset:48704
	ds_read_b128 v[128:131], v224 offset:48736
	s_waitcnt lgkmcnt(1)
	v_mfma_f32_32x32x16_bf16 v[80:95], v[120:123], v[108:111], v[80:95]
	v_lshl_add_u64 v[120:121], v[170:171], 1, s[12:13]
	v_mfma_f32_32x32x16_bf16 v[64:79], v[124:127], v[104:107], v[64:79]
	s_waitcnt lgkmcnt(0)
; __device__ __forceinline__ u16 f2bf(float f) { return (u16)(cvtpk(f, 0.f) & 0xffffu); }
; __device__ __forceinline__ void scan_chunked(const Params& p, unsigned char* smem, int bh, f32x16 (&S)[4], const int c_begin, const int c_end) {
;     ...
; #pragma unroll
;       for (int r = 0; r < 16; ++r) {
;         Oq[(8 * (r >> 2) + 4 * hf + (r & 3)) * 128 + wave * 32 + l31] = f2bf(o0[r]);
;         Oq[(32 + 8 * (r >> 2) + 4 * hf + (r & 3)) * 128 + wave * 32 + l31] = f2bf(o1[r]);
;       }
;     }
;     __builtin_amdgcn_sched_barrier(0);
;     const float cd = sSC[128 + 63];
; #pragma unroll
;     for (int dt = 0; dt < 4; ++dt)
; #pragma unroll
;       for (int r = 0; r < 16; ++r) S[dt][r] *= cd;
;     u32x4 vs[4];
; #pragma unroll
;     for (int s = 0; s < 4; ++s) {
;       const float4 e0 = *(const float4*)(sSC + 192 + 16 * s + 4 * hf), e1 = *(const float4*)(sSC + 192 + 16 * s + 8 + 4 * hf);
;       vs[s].x = cvtpk(bflo(vnf[s].x) * e0.x, bfhi(vnf[s].x) * e0.y); vs[s].y = cvtpk(bflo(vnf[s].y) * e0.z, bfhi(vnf[s].y) * e0.w);
;       vs[s].z = cvtpk(bflo(vnf[s].z) * e1.x, bfhi(vnf[s].z) * e1.y); vs[s].w = cvtpk(bflo(vnf[s].w) * e1.z, bfhi(vnf[s].w) * e1.w);
;     }
;     {
;       u32x4 id1 = {0u, 0u, 0u, 0u}, id2 = {0u, 0u, 0u, 0u};
;       {
;         const int l15 = l31 & 15;
;         const int jsel = (((l15 >> 2) & 1) == hf) ? (4 * (l15 >> 3) + (l15 & 3)) : -1;
;         const int j1 = (l31 < 16) ? jsel : -1;
;         const int j2 = (l31 >= 16) ? jsel : -1;
;         const unsigned one_lo = 0x3f80u, one_hi = 0x3f800000u;
; #pragma unroll
;         for (int w = 0; w < 4; ++w) {
;           id1[w] = (j1 == 2 * w) ? one_lo : ((j1 == 2 * w + 1) ? one_hi : 0u);
;           id2[w] = (j2 == 2 * w) ? one_lo : ((j2 == 2 * w + 1) ? one_hi : 0u);
;         }
;       }
;       const bf16x8 B1 = __builtin_bit_cast(bf16x8, id1), B2 = __builtin_bit_cast(bf16x8, id2);
; #pragma unroll
;       for (int dt = 0; dt < 4; ++dt)
; #pragma unroll
;         for (int mt = 0; mt < 2; ++mt) {
;           f32x16 kt;
; #pragma unroll
;           for (int r = 0; r < 16; ++r) kt[r] = 0.f;
;           const u16* k0 = sk + (32 * mt + l31) * 136 + 32 * dt + 8 * hf;
;           kt = mfma32(*(const bf16x8*)(k0), B1, kt);
;           kt = mfma32(*(const bf16x8*)(k0 + 16), B2, kt);
; #pragma unroll
;           for (int s2 = 0; s2 < 2; ++s2) {
	v_mfma_f32_32x32x16_bf16 v[80:95], v[128:131], v[104:107], v[80:95]
	s_nop 9
	v_cvt_pk_bf16_f32 v64, v64, s0
	global_store_short v[120:121], v64, off
	v_lshl_add_u64 v[120:121], v[172:173], 1, s[12:13]
	v_cvt_pk_bf16_f32 v66, v66, s0
	v_cvt_pk_bf16_f32 v64, v80, s0
	global_store_short v[120:121], v64, off
	v_cvt_pk_bf16_f32 v80, v65, s0
	v_lshl_add_u64 v[64:65], v[206:207], 1, s[12:13]
	global_store_short v[64:65], v80, off offset:256
	v_cvt_pk_bf16_f32 v120, v81, s0
	v_lshl_add_u64 v[80:81], v[208:209], 1, s[12:13]
	global_store_short v[80:81], v120, off offset:256
	global_store_short v[64:65], v66, off offset:512
	v_cvt_pk_bf16_f32 v66, v82, s0
	global_store_short v[80:81], v66, off offset:512
	v_cvt_pk_bf16_f32 v66, v67, s0
	global_store_short v[64:65], v66, off offset:768
	v_cvt_pk_bf16_f32 v66, v83, s0
	global_store_short v[80:81], v66, off offset:768
	v_cvt_pk_bf16_f32 v66, v68, s0
	global_store_short v[64:65], v66, off offset:2048
	v_cvt_pk_bf16_f32 v66, v84, s0
	global_store_short v[80:81], v66, off offset:2048
	v_cvt_pk_bf16_f32 v66, v69, s0
	global_store_short v[64:65], v66, off offset:2304
	v_cvt_pk_bf16_f32 v66, v85, s0
	global_store_short v[80:81], v66, off offset:2304
	v_cvt_pk_bf16_f32 v66, v70, s0
	global_store_short v[64:65], v66, off offset:2560
	v_cvt_pk_bf16_f32 v66, v86, s0
	global_store_short v[80:81], v66, off offset:2560
	v_cvt_pk_bf16_f32 v66, v71, s0
	global_store_short v[64:65], v66, off offset:2816
	v_cvt_pk_bf16_f32 v64, v87, s0
	global_store_short v[80:81], v64, off offset:2816
	v_cvt_pk_bf16_f32 v66, v72, s0
	v_lshl_add_u64 v[64:65], v[174:175], 1, s[12:13]
	global_store_short v[64:65], v66, off
	v_cvt_pk_bf16_f32 v66, v88, s0
	v_lshl_add_u64 v[64:65], v[176:177], 1, s[12:13]
	global_store_short v[64:65], v66, off
	v_cvt_pk_bf16_f32 v66, v73, s0
	v_lshl_add_u64 v[64:65], v[178:179], 1, s[12:13]
	global_store_short v[64:65], v66, off
	v_cvt_pk_bf16_f32 v66, v89, s0
	v_lshl_add_u64 v[64:65], v[180:181], 1, s[12:13]
	global_store_short v[64:65], v66, off
	v_cvt_pk_bf16_f32 v66, v74, s0
	v_lshl_add_u64 v[64:65], v[182:183], 1, s[12:13]
	global_store_short v[64:65], v66, off
	v_cvt_pk_bf16_f32 v66, v90, s0
	v_lshl_add_u64 v[64:65], v[184:185], 1, s[12:13]
	global_store_short v[64:65], v66, off
	v_cvt_pk_bf16_f32 v66, v75, s0
	v_lshl_add_u64 v[64:65], v[186:187], 1, s[12:13]
	global_store_short v[64:65], v66, off
	v_cvt_pk_bf16_f32 v66, v91, s0
	v_lshl_add_u64 v[64:65], v[188:189], 1, s[12:13]
	global_store_short v[64:65], v66, off
	v_cvt_pk_bf16_f32 v66, v76, s0
	v_lshl_add_u64 v[64:65], v[190:191], 1, s[12:13]
	global_store_short v[64:65], v66, off
	v_cvt_pk_bf16_f32 v66, v92, s0
	v_lshl_add_u64 v[64:65], v[192:193], 1, s[12:13]
	global_store_short v[64:65], v66, off
	v_cvt_pk_bf16_f32 v66, v77, s0
	v_lshl_add_u64 v[64:65], v[194:195], 1, s[12:13]
	global_store_short v[64:65], v66, off
	v_cvt_pk_bf16_f32 v66, v93, s0
	v_lshl_add_u64 v[64:65], v[196:197], 1, s[12:13]
	global_store_short v[64:65], v66, off
	v_cvt_pk_bf16_f32 v66, v78, s0
	v_lshl_add_u64 v[64:65], v[198:199], 1, s[12:13]
	global_store_short v[64:65], v66, off
	v_cvt_pk_bf16_f32 v66, v94, s0
	v_lshl_add_u64 v[64:65], v[200:201], 1, s[12:13]
	global_store_short v[64:65], v66, off
	v_cvt_pk_bf16_f32 v66, v79, s0
	v_lshl_add_u64 v[64:65], v[202:203], 1, s[12:13]
	global_store_short v[64:65], v66, off
	v_cvt_pk_bf16_f32 v66, v95, s0
	v_lshl_add_u64 v[64:65], v[204:205], 1, s[12:13]
	global_store_short v[64:65], v66, off
	ds_read_b32 v92, v161 offset:54012
	ds_read_b128 v[226:229], v159
	ds_read_b128 v[230:233], v159 offset:32
	ds_read_b128 v[234:237], v159 offset:8704
	ds_read_b128 v[238:241], v159 offset:8736
	ds_read_b128 v[64:67], v222 offset:54016
	ds_read_b128 v[68:71], v222 offset:54048
	ds_read_b128 v[72:75], v222 offset:54080
	ds_read_b128 v[76:79], v222 offset:54112
	s_waitcnt lgkmcnt(7)
	v_mfma_f32_32x32x16_bf16 v[120:135], v[226:229], v[96:99], 0
	s_waitcnt lgkmcnt(6)
	v_mfma_f32_32x32x16_bf16 v[120:135], v[230:233], v[100:103], v[120:135]
	s_waitcnt lgkmcnt(5)
	v_mfma_f32_32x32x16_bf16 v[136:151], v[234:237], v[96:99], 0
	s_waitcnt lgkmcnt(4)
	v_mfma_f32_32x32x16_bf16 v[136:151], v[238:241], v[100:103], v[136:151]
	ds_read_b128 v[226:229], v159 offset:64
	ds_read_b128 v[230:233], v159 offset:96
	ds_read_b128 v[234:237], v159 offset:8768
	ds_read_b128 v[238:241], v159 offset:8800
	v_pk_mul_f32 v[62:63], v[62:63], v[92:93] op_sel_hi:[1,0]
	v_pk_mul_f32 v[60:61], v[60:61], v[92:93] op_sel_hi:[1,0]
	v_pk_mul_f32 v[58:59], v[58:59], v[92:93] op_sel_hi:[1,0]
	v_pk_mul_f32 v[56:57], v[56:57], v[92:93] op_sel_hi:[1,0]
	v_pk_mul_f32 v[54:55], v[54:55], v[92:93] op_sel_hi:[1,0]
	v_pk_mul_f32 v[52:53], v[52:53], v[92:93] op_sel_hi:[1,0]
	v_pk_mul_f32 v[50:51], v[50:51], v[92:93] op_sel_hi:[1,0]
	v_pk_mul_f32 v[48:49], v[48:49], v[92:93] op_sel_hi:[1,0]
	v_lshlrev_b32_e32 v242, 16, v116
	v_and_b32_e32 v243, 0xffff0000, v116
	s_waitcnt lgkmcnt(7)
	v_pk_mul_f32 v[242:243], v[64:65], v[242:243]
	v_cvt_pk_bf16_f32 v80, v242, v243
	v_lshlrev_b32_e32 v244, 16, v117
	v_and_b32_e32 v245, 0xffff0000, v117
	v_pk_mul_f32 v[244:245], v[66:67], v[244:245]
	v_cvt_pk_bf16_f32 v81, v244, v245
	v_lshlrev_b32_e32 v242, 16, v118
	v_and_b32_e32 v243, 0xffff0000, v118
	s_waitcnt lgkmcnt(6)
	v_pk_mul_f32 v[242:243], v[68:69], v[242:243]
	v_cvt_pk_bf16_f32 v82, v242, v243
	v_lshlrev_b32_e32 v244, 16, v119
	v_and_b32_e32 v245, 0xffff0000, v119
	v_pk_mul_f32 v[244:245], v[70:71], v[244:245]
	v_cvt_pk_bf16_f32 v83, v244, v245
	v_lshlrev_b32_e32 v242, 16, v112
	v_and_b32_e32 v243, 0xffff0000, v112
	s_waitcnt lgkmcnt(5)
; __device__ __forceinline__ unsigned cvtpk(float lo, float hi) { f32x2_t v = {lo, hi}; bf16x2_t b = __builtin_convertvector(v, bf16x2_t); return __builtin_bit_cast(unsigned, b); }
; __device__ __forceinline__ float bflo(unsigned v) { return __uint_as_float(v << 16); }
; __device__ __forceinline__ void scan_chunked(const Params& p, unsigned char* smem, int bh, f32x16 (&S)[4], const int c_begin, const int c_end) {
;     ...
;     u32x4 vs[4];
; #pragma unroll
;     for (int s = 0; s < 4; ++s) {
;       const float4 e0 = *(const float4*)(sSC + 192 + 16 * s + 4 * hf), e1 = *(const float4*)(sSC + 192 + 16 * s + 8 + 4 * hf);
;       vs[s].x = cvtpk(bflo(vnf[s].x) * e0.x, bfhi(vnf[s].x) * e0.y); vs[s].y = cvtpk(bflo(vnf[s].y) * e0.z, bfhi(vnf[s].y) * e0.w);
;       vs[s].z = cvtpk(bflo(vnf[s].z) * e1.x, bfhi(vnf[s].z) * e1.y); vs[s].w = cvtpk(bflo(vnf[s].w) * e1.z, bfhi(vnf[s].w) * e1.w);
;     }
;     {
;       u32x4 id1 = {0u, 0u, 0u, 0u}, id2 = {0u, 0u, 0u, 0u};
;       {
;         const int l15 = l31 & 15;
;         const int jsel = (((l15 >> 2) & 1) == hf) ? (4 * (l15 >> 3) + (l15 & 3)) : -1;
;         const int j1 = (l31 < 16) ? jsel : -1;
;         const int j2 = (l31 >= 16) ? jsel : -1;
;         const unsigned one_lo = 0x3f80u, one_hi = 0x3f800000u;
; #pragma unroll
;         for (int w = 0; w < 4; ++w) {
;           id1[w] = (j1 == 2 * w) ? one_lo : ((j1 == 2 * w + 1) ? one_hi : 0u);
;           id2[w] = (j2 == 2 * w) ? one_lo : ((j2 == 2 * w + 1) ? one_hi : 0u);
;         }
;       }
;       const bf16x8 B1 = __builtin_bit_cast(bf16x8, id1), B2 = __builtin_bit_cast(bf16x8, id2);
; #pragma unroll
;       for (int dt = 0; dt < 4; ++dt)
; #pragma unroll
;         for (int mt = 0; mt < 2; ++mt) {
;           f32x16 kt;
; #pragma unroll
;           for (int r = 0; r < 16; ++r) kt[r] = 0.f;
;           const u16* k0 = sk + (32 * mt + l31) * 136 + 32 * dt + 8 * hf;
;           kt = mfma32(*(const bf16x8*)(k0), B1, kt);
;           kt = mfma32(*(const bf16x8*)(k0 + 16), B2, kt);
; #pragma unroll
;           for (int s2 = 0; s2 < 2; ++s2) {
;             u32x4 af = {cvtpk(kt[8 * s2 + 0], kt[8 * s2 + 1]), cvtpk(kt[8 * s2 + 2], kt[8 * s2 + 3]), cvtpk(kt[8 * s2 + 4], kt[8 * s2 + 5]), cvtpk(kt[8 * s2 + 6], kt[8 * s2 + 7])};
;             S[dt] = mfma32(__builtin_bit_cast(bf16x8, af), __builtin_bit_cast(bf16x8, vs[2 * mt + s2]), S[dt]);
;           }
;         }
	v_pk_mul_f32 v[242:243], v[72:73], v[242:243]
	v_cvt_pk_bf16_f32 v84, v242, v243
	v_lshlrev_b32_e32 v244, 16, v113
	v_and_b32_e32 v245, 0xffff0000, v113
	v_pk_mul_f32 v[244:245], v[74:75], v[244:245]
	v_cvt_pk_bf16_f32 v85, v244, v245
	v_lshlrev_b32_e32 v242, 16, v114
	v_and_b32_e32 v243, 0xffff0000, v114
	s_waitcnt lgkmcnt(4)
	v_pk_mul_f32 v[242:243], v[76:77], v[242:243]
	v_cvt_pk_bf16_f32 v86, v242, v243
	v_lshlrev_b32_e32 v244, 16, v115
	v_and_b32_e32 v245, 0xffff0000, v115
	v_pk_mul_f32 v[244:245], v[78:79], v[244:245]
	v_cvt_pk_bf16_f32 v87, v244, v245
	ds_read_b128 v[64:67], v222 offset:54144
	ds_read_b128 v[68:71], v222 offset:54176
	ds_read_b128 v[72:75], v222 offset:54208
	ds_read_b128 v[76:79], v222 offset:54240
	v_cvt_pk_bf16_f32 v120, v120, v121
	v_cvt_pk_bf16_f32 v121, v122, v123
	v_cvt_pk_bf16_f32 v122, v124, v125
	v_cvt_pk_bf16_f32 v123, v126, v127
	s_nop 1
	v_mfma_f32_32x32x16_bf16 v[48:63], v[120:123], v[80:83], v[48:63]
	v_cvt_pk_bf16_f32 v124, v128, v129
	v_cvt_pk_bf16_f32 v125, v130, v131
	v_cvt_pk_bf16_f32 v126, v132, v133
	v_cvt_pk_bf16_f32 v127, v134, v135
	s_nop 1
	v_mfma_f32_32x32x16_bf16 v[48:63], v[124:127], v[84:87], v[48:63]
	s_waitcnt lgkmcnt(7)
	v_mfma_f32_32x32x16_bf16 v[120:135], v[226:229], v[96:99], 0
	s_waitcnt lgkmcnt(6)
	v_mfma_f32_32x32x16_bf16 v[120:135], v[230:233], v[100:103], v[120:135]
	v_lshlrev_b32_e32 v242, 16, v108
	v_and_b32_e32 v243, 0xffff0000, v108
	s_waitcnt lgkmcnt(3)
	v_pk_mul_f32 v[242:243], v[64:65], v[242:243]
	v_cvt_pk_bf16_f32 v88, v242, v243
	v_lshlrev_b32_e32 v244, 16, v109
	v_and_b32_e32 v245, 0xffff0000, v109
	v_pk_mul_f32 v[244:245], v[66:67], v[244:245]
	v_cvt_pk_bf16_f32 v89, v244, v245
	v_lshlrev_b32_e32 v242, 16, v110
	v_and_b32_e32 v243, 0xffff0000, v110
	s_waitcnt lgkmcnt(2)
	v_pk_mul_f32 v[242:243], v[68:69], v[242:243]
	v_cvt_pk_bf16_f32 v90, v242, v243
	v_lshlrev_b32_e32 v244, 16, v111
	v_and_b32_e32 v245, 0xffff0000, v111
	v_pk_mul_f32 v[244:245], v[70:71], v[244:245]
	v_cvt_pk_bf16_f32 v91, v244, v245
	v_lshlrev_b32_e32 v242, 16, v104
	v_and_b32_e32 v243, 0xffff0000, v104
	s_waitcnt lgkmcnt(1)
	v_pk_mul_f32 v[242:243], v[72:73], v[242:243]
	v_cvt_pk_bf16_f32 v104, v242, v243
	v_lshlrev_b32_e32 v244, 16, v105
	v_and_b32_e32 v245, 0xffff0000, v105
	v_pk_mul_f32 v[244:245], v[74:75], v[244:245]
	v_cvt_pk_bf16_f32 v105, v244, v245
	v_lshlrev_b32_e32 v242, 16, v106
	v_and_b32_e32 v243, 0xffff0000, v106
	s_waitcnt lgkmcnt(0)
	v_pk_mul_f32 v[242:243], v[76:77], v[242:243]
	v_cvt_pk_bf16_f32 v106, v242, v243
	v_lshlrev_b32_e32 v244, 16, v107
	v_and_b32_e32 v245, 0xffff0000, v107
	v_pk_mul_f32 v[244:245], v[78:79], v[244:245]
	v_cvt_pk_bf16_f32 v107, v244, v245
	v_pk_mul_f32 v[46:47], v[46:47], v[92:93] op_sel_hi:[1,0]
	v_pk_mul_f32 v[44:45], v[44:45], v[92:93] op_sel_hi:[1,0]
	v_pk_mul_f32 v[42:43], v[42:43], v[92:93] op_sel_hi:[1,0]
	v_pk_mul_f32 v[40:41], v[40:41], v[92:93] op_sel_hi:[1,0]
	v_pk_mul_f32 v[38:39], v[38:39], v[92:93] op_sel_hi:[1,0]
	v_pk_mul_f32 v[36:37], v[36:37], v[92:93] op_sel_hi:[1,0]
	v_pk_mul_f32 v[34:35], v[34:35], v[92:93] op_sel_hi:[1,0]
	v_pk_mul_f32 v[32:33], v[32:33], v[92:93] op_sel_hi:[1,0]
	v_cvt_pk_bf16_f32 v136, v136, v137
	v_cvt_pk_bf16_f32 v137, v138, v139
	v_cvt_pk_bf16_f32 v138, v140, v141
	v_cvt_pk_bf16_f32 v139, v142, v143
	s_nop 1
	v_mfma_f32_32x32x16_bf16 v[48:63], v[136:139], v[88:91], v[48:63]
	v_cvt_pk_bf16_f32 v140, v144, v145
	v_cvt_pk_bf16_f32 v141, v146, v147
	v_cvt_pk_bf16_f32 v142, v148, v149
	v_cvt_pk_bf16_f32 v143, v150, v151
	s_nop 1
	v_mfma_f32_32x32x16_bf16 v[48:63], v[140:143], v[104:107], v[48:63]
	v_mfma_f32_32x32x16_bf16 v[136:151], v[234:237], v[96:99], 0
	v_mfma_f32_32x32x16_bf16 v[136:151], v[238:241], v[100:103], v[136:151]
	ds_read_b128 v[226:229], v159 offset:128
	ds_read_b128 v[230:233], v159 offset:160
	ds_read_b128 v[234:237], v159 offset:8832
	ds_read_b128 v[238:241], v159 offset:8864
	v_pk_mul_f32 v[30:31], v[30:31], v[92:93] op_sel_hi:[1,0]
	v_pk_mul_f32 v[28:29], v[28:29], v[92:93] op_sel_hi:[1,0]
	v_pk_mul_f32 v[26:27], v[26:27], v[92:93] op_sel_hi:[1,0]
	v_pk_mul_f32 v[24:25], v[24:25], v[92:93] op_sel_hi:[1,0]
	v_pk_mul_f32 v[22:23], v[22:23], v[92:93] op_sel_hi:[1,0]
	v_pk_mul_f32 v[20:21], v[20:21], v[92:93] op_sel_hi:[1,0]
	v_pk_mul_f32 v[18:19], v[18:19], v[92:93] op_sel_hi:[1,0]
	v_pk_mul_f32 v[16:17], v[16:17], v[92:93] op_sel_hi:[1,0]
	v_cvt_pk_bf16_f32 v120, v120, v121
	v_cvt_pk_bf16_f32 v121, v122, v123
	v_cvt_pk_bf16_f32 v122, v124, v125
	v_cvt_pk_bf16_f32 v123, v126, v127
	s_nop 1
	v_mfma_f32_32x32x16_bf16 v[32:47], v[120:123], v[80:83], v[32:47]
	v_cvt_pk_bf16_f32 v124, v128, v129
	v_cvt_pk_bf16_f32 v125, v130, v131
	v_cvt_pk_bf16_f32 v126, v132, v133
	v_cvt_pk_bf16_f32 v127, v134, v135
	s_nop 1
	v_mfma_f32_32x32x16_bf16 v[32:47], v[124:127], v[84:87], v[32:47]
	s_waitcnt lgkmcnt(3)
; __device__ __forceinline__ unsigned cvtpk(float lo, float hi) { f32x2_t v = {lo, hi}; bf16x2_t b = __builtin_convertvector(v, bf16x2_t); return __builtin_bit_cast(unsigned, b); }
; __device__ __forceinline__ f32x16 mfma32(bf16x8 a, bf16x8 b, f32x16 c) { return __builtin_amdgcn_mfma_f32_32x32x16_bf16(a, b, c, 0, 0, 0); }
; __device__ __forceinline__ void lds_barrier() { asm volatile("s_waitcnt lgkmcnt(0)\n\ts_barrier" ::: "memory"); }
; __device__ __forceinline__ void scan_chunked(const Params& p, unsigned char* smem, int bh, f32x16 (&S)[4], const int c_begin, const int c_end) {
;     ...
; #pragma unroll 1
;   for (int c = c_begin; c < c_end; ++c) {
;     if (c >= P2_SPLIT && (c & 7) == 0) {
;       const unsigned need = (c == 128) ? 1u : 8u;
;       if (tid == 0) {
;         const unsigned* f = (const unsigned*)(p.ws + OFF_BAR) + 16 + bh * 17 + (c >> 3);
;         while (__hip_atomic_load(f, __ATOMIC_RELAXED, __HIP_MEMORY_SCOPE_AGENT) < need) __builtin_amdgcn_s_sleep(2);
;         __builtin_amdgcn_fence(__ATOMIC_ACQUIRE, "agent");
;       }
;       __syncthreads();
;     }
;     ...
; #pragma unroll
;       for (int dt = 0; dt < 4; ++dt)
; #pragma unroll
;         for (int mt = 0; mt < 2; ++mt) {
;           f32x16 kt;
; #pragma unroll
;           for (int r = 0; r < 16; ++r) kt[r] = 0.f;
;           const u16* k0 = sk + (32 * mt + l31) * 136 + 32 * dt + 8 * hf;
;           kt = mfma32(*(const bf16x8*)(k0), B1, kt);
;           kt = mfma32(*(const bf16x8*)(k0 + 16), B2, kt);
; #pragma unroll
;           for (int s2 = 0; s2 < 2; ++s2) {
;             u32x4 af = {cvtpk(kt[8 * s2 + 0], kt[8 * s2 + 1]), cvtpk(kt[8 * s2 + 2], kt[8 * s2 + 3]), cvtpk(kt[8 * s2 + 4], kt[8 * s2 + 5]), cvtpk(kt[8 * s2 + 6], kt[8 * s2 + 7])};
;             S[dt] = mfma32(__builtin_bit_cast(bf16x8, af), __builtin_bit_cast(bf16x8, vs[2 * mt + s2]), S[dt]);
;           }
;         }
;     }
;     lds_barrier();
	v_mfma_f32_32x32x16_bf16 v[120:135], v[226:229], v[96:99], 0
	s_waitcnt lgkmcnt(2)
	v_mfma_f32_32x32x16_bf16 v[120:135], v[230:233], v[100:103], v[120:135]
	v_pk_mul_f32 v[14:15], v[14:15], v[92:93] op_sel_hi:[1,0]
	v_pk_mul_f32 v[12:13], v[12:13], v[92:93] op_sel_hi:[1,0]
	v_pk_mul_f32 v[10:11], v[10:11], v[92:93] op_sel_hi:[1,0]
	v_pk_mul_f32 v[8:9], v[8:9], v[92:93] op_sel_hi:[1,0]
	v_pk_mul_f32 v[6:7], v[6:7], v[92:93] op_sel_hi:[1,0]
	v_pk_mul_f32 v[4:5], v[4:5], v[92:93] op_sel_hi:[1,0]
	v_pk_mul_f32 v[2:3], v[2:3], v[92:93] op_sel_hi:[1,0]
	v_pk_mul_f32 v[0:1], v[0:1], v[92:93] op_sel_hi:[1,0]
	v_cvt_pk_bf16_f32 v136, v136, v137
	v_cvt_pk_bf16_f32 v137, v138, v139
	v_cvt_pk_bf16_f32 v138, v140, v141
	v_cvt_pk_bf16_f32 v139, v142, v143
	s_nop 1
	v_mfma_f32_32x32x16_bf16 v[32:47], v[136:139], v[88:91], v[32:47]
	v_cvt_pk_bf16_f32 v140, v144, v145
	v_cvt_pk_bf16_f32 v141, v146, v147
	v_cvt_pk_bf16_f32 v142, v148, v149
	v_cvt_pk_bf16_f32 v143, v150, v151
	s_nop 1
	v_mfma_f32_32x32x16_bf16 v[32:47], v[140:143], v[104:107], v[32:47]
	s_waitcnt lgkmcnt(1)
	v_mfma_f32_32x32x16_bf16 v[136:151], v[234:237], v[96:99], 0
	s_waitcnt lgkmcnt(0)
	v_mfma_f32_32x32x16_bf16 v[136:151], v[238:241], v[100:103], v[136:151]
	ds_read_b128 v[226:229], v159 offset:192
	ds_read_b128 v[230:233], v159 offset:224
	ds_read_b128 v[234:237], v159 offset:8896
	ds_read_b128 v[238:241], v159 offset:8928
	v_cvt_pk_bf16_f32 v120, v120, v121
	v_cvt_pk_bf16_f32 v121, v122, v123
	v_cvt_pk_bf16_f32 v122, v124, v125
	v_cvt_pk_bf16_f32 v123, v126, v127
	s_nop 1
	v_mfma_f32_32x32x16_bf16 v[16:31], v[120:123], v[80:83], v[16:31]
	v_cvt_pk_bf16_f32 v124, v128, v129
	v_cvt_pk_bf16_f32 v125, v130, v131
	v_cvt_pk_bf16_f32 v126, v132, v133
	v_cvt_pk_bf16_f32 v127, v134, v135
	s_nop 1
	v_mfma_f32_32x32x16_bf16 v[16:31], v[124:127], v[84:87], v[16:31]
	s_waitcnt lgkmcnt(3)
	v_mfma_f32_32x32x16_bf16 v[120:135], v[226:229], v[96:99], 0
	s_waitcnt lgkmcnt(2)
	v_mfma_f32_32x32x16_bf16 v[120:135], v[230:233], v[100:103], v[120:135]
	v_cvt_pk_bf16_f32 v136, v136, v137
	v_cvt_pk_bf16_f32 v137, v138, v139
	v_cvt_pk_bf16_f32 v138, v140, v141
	v_cvt_pk_bf16_f32 v139, v142, v143
	s_nop 1
	v_mfma_f32_32x32x16_bf16 v[16:31], v[136:139], v[88:91], v[16:31]
	v_cvt_pk_bf16_f32 v140, v144, v145
	v_cvt_pk_bf16_f32 v141, v146, v147
	v_cvt_pk_bf16_f32 v142, v148, v149
	v_cvt_pk_bf16_f32 v143, v150, v151
	s_nop 1
	v_mfma_f32_32x32x16_bf16 v[16:31], v[140:143], v[104:107], v[16:31]
	s_waitcnt lgkmcnt(1)
	v_mfma_f32_32x32x16_bf16 v[136:151], v[234:237], v[96:99], 0
	s_waitcnt lgkmcnt(0)
	v_mfma_f32_32x32x16_bf16 v[136:151], v[238:241], v[100:103], v[136:151]
	s_waitcnt lgkmcnt(0)
	s_barrier
	v_cvt_pk_bf16_f32 v120, v120, v121
	v_cvt_pk_bf16_f32 v121, v122, v123
	v_cvt_pk_bf16_f32 v122, v124, v125
	v_cvt_pk_bf16_f32 v123, v126, v127
	s_nop 1
	v_mfma_f32_32x32x16_bf16 v[0:15], v[120:123], v[80:83], v[0:15]
	v_cvt_pk_bf16_f32 v124, v128, v129
	v_cvt_pk_bf16_f32 v125, v130, v131
	v_cvt_pk_bf16_f32 v126, v132, v133
	v_cvt_pk_bf16_f32 v127, v134, v135
	s_nop 1
	v_mfma_f32_32x32x16_bf16 v[0:15], v[124:127], v[84:87], v[0:15]
	v_cvt_pk_bf16_f32 v136, v136, v137
	v_cvt_pk_bf16_f32 v137, v138, v139
	v_cvt_pk_bf16_f32 v138, v140, v141
	v_cvt_pk_bf16_f32 v139, v142, v143
	s_nop 1
	v_mfma_f32_32x32x16_bf16 v[0:15], v[136:139], v[88:91], v[0:15]
	v_cvt_pk_bf16_f32 v140, v144, v145
	v_cvt_pk_bf16_f32 v141, v146, v147
	v_cvt_pk_bf16_f32 v142, v148, v149
	v_cvt_pk_bf16_f32 v143, v150, v151
	s_nop 1
	v_mfma_f32_32x32x16_bf16 v[0:15], v[140:143], v[104:107], v[0:15]
	s_add_i32 s7, s7, 1
	s_cmpk_eq_i32 s7, 0x81
	s_cbranch_scc1 .LBB0_320
.LBB0_316:
	s_and_b32 s12, s7, 7
	s_cmp_lg_u32 s12, 0
	s_cbranch_scc1 .LBB0_315
	s_and_saveexec_b64 s[12:13], s[4:5]
	s_cbranch_execz .LBB0_314
	s_cmpk_eq_i32 s7, 0x80
	s_cselect_b32 s21, 1, 8
	s_lshr_b32 s14, s7, 1
	s_add_u32 s14, s8, s14
	s_addc_u32 s15, s9, 0
	s_waitcnt vmcnt(0)
	v_cmp_le_u32_e32 vcc, s21, v225
	s_cbranch_vccnz .LBB0_313
